# stack + P0: odd waves run the W_f fold before the streaming loops
# baseline (speedup 1.0000x reference)
.LBB0_8:
	s_or_b64 exec, exec, s[0:1]
	s_lshl_b32 s0, s2, 3
	s_add_i32 s16, s84, s0
	s_lshl_b32 s17, s3, 3
	s_mov_b32 s99, s16
	s_and_b32 s98, s84, 1
	s_waitcnt lgkmcnt(0)
	s_barrier
	s_cmp_eq_u32 s98, 1
	s_cbranch_scc1 .LBB0_22
.Lp0_main:
	s_cmpk_gt_i32 s16, 0xcff
	s_cbranch_scc1 .LBB0_15
	s_lshl_b32 s0, s84, 14
	v_lshlrev_b32_e32 v2, 4, v216
	v_lshlrev_b32_e32 v6, 3, v216
	s_add_i32 s0, s0, 0
	v_lshrrev_b32_e32 v1, 3, v128
	v_and_b32_e32 v2, 0x70, v2
	v_and_b32_e32 v6, 56, v6
	v_mov_b32_e32 v3, 0
	v_add_u32_e32 v16, s0, v2
	v_mul_u32_u24_e32 v17, 0x84, v1
	v_mul_u32_u24_e32 v8, 0x84, v6
	v_readlane_b32 s6, v255, 1
	v_lshlrev_b32_e32 v9, 2, v1
	v_lshlrev_b32_e32 v10, 1, v6
	v_mov_b32_e32 v11, v3
	v_readlane_b32 s7, v255, 2
	v_add3_u32 v15, s0, v8, v9
	s_lshl_b32 s0, s16, 1
	v_add_u32_e32 v16, v16, v17
	s_mov_b32 s1, 0
	v_lshl_add_u64 v[4:5], s[62:63], 0, v[2:3]
	v_or_b32_e32 v12, 8, v1
	v_or_b32_e32 v13, 16, v1
	v_or_b32_e32 v14, 24, v1
	v_lshl_add_u64 v[6:7], s[6:7], 0, v[10:11]
	v_lshl_add_u64 v[8:9], s[46:47], 0, v[2:3]
	v_lshl_add_u64 v[10:11], s[80:81], 0, v[10:11]
	s_lshl_b32 s8, s16, 5
	s_lshl_b32 s9, s17, 5
	s_add_i32 s10, s0, 0x1ea00
	s_lshl_b32 s11, s17, 1
	v_add_u32_e32 v17, 0x420, v16
	v_add_u32_e32 v18, 0x428, v16
	v_add_u32_e32 v19, 0x840, v16
	v_add_u32_e32 v20, 0x848, v16
	v_add_u32_e32 v21, 0xc60, v16
	v_add_u32_e32 v22, 0xc68, v16
	v_add_u32_e32 v23, 0x1080, v16
	v_add_u32_e32 v24, 0x1088, v16
	v_add_u32_e32 v25, 0x14a0, v16
	v_add_u32_e32 v26, 0x14a8, v16
	v_add_u32_e32 v27, 0x18c0, v16
	v_add_u32_e32 v28, 0x18c8, v16
	v_add_u32_e32 v29, 0x1ce0, v16
	v_add_u32_e32 v30, 0x1ce8, v16
	s_movk_i32 s12, 0x7fff
	s_mov_b32 s13, 0xffff0000
	s_movk_i32 s14, 0x5800
	s_mov_b32 s15, s16
	s_branch .LBB0_11

.LBB0_22:
	s_cmp_eq_u32 s98, 2
	s_cbranch_scc1 .LBB0_27
	v_readlane_b32 s26, v255, 5
	s_cmpk_gt_i32 s16, 0x7ff
	v_readlane_b32 s27, v255, 6
	s_cbranch_scc1 .LBB0_27
	v_and_b32_e32 v10, 15, v216
	v_lshlrev_b32_e32 v2, 1, v216
	s_lshl_b32 s0, s2, 7
	s_lshl_b32 s1, s84, 4
	v_lshrrev_b32_e32 v1, 4, v128
	v_mov_b32_e32 v13, 0
	v_and_b32_e32 v2, 6, v2
	s_add_i32 s6, s0, s1
	v_lshlrev_b32_e32 v12, 2, v10
	s_lshl_b32 s0, s2, 4
	s_lshl_b32 s1, s84, 1
	v_lshlrev_b32_e32 v11, 13, v1
	v_or_b32_e32 v20, 28, v1
	s_lshl_b32 s7, s3, 7
	v_lshlrev_b32_e32 v21, 5, v10
	v_lshl_add_u64 v[14:15], s[58:59], 0, v[12:13]
	s_add_i32 s8, s0, s1
	s_lshl_b32 s9, s3, 4
	v_or_b32_e32 v22, 24, v1
	v_or_b32_e32 v23, 20, v1
	v_or_b32_e32 v24, 16, v1
	v_or_b32_e32 v25, 12, v1
	v_or_b32_e32 v26, 8, v1
	v_or_b32_e32 v27, 4, v1
	s_add_i32 s10, 0, 0x20000
	s_movk_i32 s11, 0x4000
	s_mov_b32 s12, 0x8000
	s_mov_b32 s13, 0xc000
	s_mov_b32 s14, 0x10000
	s_mov_b32 s15, 0x14000
	s_mov_b32 s18, 0x18000
	s_mov_b32 s19, 0x1c000
	v_lshlrev_b32_e32 v16, 1, v2
	s_movk_i32 s20, 0x7fff
	s_mov_b32 s21, 0xffff0000
	s_movk_i32 s22, 0x1000
	s_movk_i32 s23, 0x2000
	v_lshlrev_b32_e32 v28, 1, v10
	v_mov_b32_e32 v29, 0xf8
	v_mov_b32_e32 v17, v13

.LBB0_27:
	s_cmp_eq_u32 s98, 1
	s_cbranch_scc0 .Lp0_after_fold
	s_mov_b32 s98, 2
	s_mov_b32 s16, s99
	s_branch .Lp0_main

	.amdhsa_kernel _Z10fwd_kernel6Params
		.amdhsa_group_segment_fixed_size 0
		.amdhsa_private_segment_fixed_size 0
		.amdhsa_kernarg_size 432
		.amdhsa_user_sgpr_count 2
		.amdhsa_user_sgpr_dispatch_ptr 0
		.amdhsa_user_sgpr_queue_ptr 0
		.amdhsa_user_sgpr_kernarg_segment_ptr 1
		.amdhsa_user_sgpr_dispatch_id 0
		.amdhsa_user_sgpr_kernarg_preload_length 0
		.amdhsa_user_sgpr_kernarg_preload_offset 0
		.amdhsa_user_sgpr_private_segment_size 0
		.amdhsa_uses_dynamic_stack 0
		.amdhsa_enable_private_segment 0
		.amdhsa_system_sgpr_workgroup_id_x 1
		.amdhsa_system_sgpr_workgroup_id_y 0
		.amdhsa_system_sgpr_workgroup_id_z 0
		.amdhsa_system_sgpr_workgroup_info 0
		.amdhsa_system_vgpr_workitem_id 2
		.amdhsa_next_free_vgpr 256
		.amdhsa_next_free_sgpr 102
		.amdhsa_accum_offset 256
		.amdhsa_reserve_vcc 1
		.amdhsa_float_round_mode_32 0
		.amdhsa_float_round_mode_16_64 0
		.amdhsa_float_denorm_mode_32 3
		.amdhsa_float_denorm_mode_16_64 3
		.amdhsa_dx10_clamp 1
		.amdhsa_ieee_mode 1
		.amdhsa_fp16_overflow 0
		.amdhsa_tg_split 0
		.amdhsa_exception_fp_ieee_invalid_op 0
		.amdhsa_exception_fp_denorm_src 0
		.amdhsa_exception_fp_ieee_div_zero 0
		.amdhsa_exception_fp_ieee_overflow 0
		.amdhsa_exception_fp_ieee_underflow 0
		.amdhsa_exception_fp_ieee_inexact 0
		.amdhsa_exception_int_div_zero 0
	.end_amdhsa_kernel

amdhsa.kernels:
  - .agpr_count:     0
    .args:
      - .offset:         0
        .size:           176
        .value_kind:     by_value
      - .offset:         176
        .size:           4
        .value_kind:     hidden_block_count_x
      - .offset:         180
        .size:           4
        .value_kind:     hidden_block_count_y
      - .offset:         184
        .size:           4
        .value_kind:     hidden_block_count_z
      - .offset:         188
        .size:           2
        .value_kind:     hidden_group_size_x
      - .offset:         190
        .size:           2
        .value_kind:     hidden_group_size_y
      - .offset:         192
        .size:           2
        .value_kind:     hidden_group_size_z
      - .offset:         194
        .size:           2
        .value_kind:     hidden_remainder_x
      - .offset:         196
        .size:           2
        .value_kind:     hidden_remainder_y
      - .offset:         198
        .size:           2
        .value_kind:     hidden_remainder_z
      - .offset:         216
        .size:           8
        .value_kind:     hidden_global_offset_x
      - .offset:         224
        .size:           8
        .value_kind:     hidden_global_offset_y
      - .offset:         232
        .size:           8
        .value_kind:     hidden_global_offset_z
      - .offset:         240
        .size:           2
        .value_kind:     hidden_grid_dims
      - .offset:         264
        .size:           8
        .value_kind:     hidden_multigrid_sync_arg
      - .offset:         296
        .size:           4
        .value_kind:     hidden_dynamic_lds_size
    .group_segment_fixed_size: 0
    .kernarg_segment_align: 8
    .kernarg_segment_size: 432
    .language:       OpenCL C
    .language_version:
      - 2
      - 0
    .max_flat_workgroup_size: 512
    .name:           _Z10fwd_kernel6Params
    .private_segment_fixed_size: 0
    .sgpr_count:     108
    .sgpr_spill_count: 51
    .symbol:         _Z10fwd_kernel6Params.kd
    .uniform_work_group_size: 1
    .uses_dynamic_stack: false
    .vgpr_count:     256
    .vgpr_spill_count: 0
    .wavefront_size: 64
